# HGRN pass-1 item: v rows prefetched one item ahead with the k rows (scalar base shared, loop-invariant lane offsets), packed at the item tail
# speedup vs baseline: 1.0048x; 1.0005x over previous
; DEV void hg_load_k(const u16* __restrict__ zb, int tid, u16 (&kr)[16]) {
;   const int wid = tid >> 6, lane = tid & 63, dir = wid >> 2, qu = wid & 3;
;   const u16* kp = zb + (long)(qu * 16) * NINP + C_HF + dir * 512 + lane;
; #pragma unroll
;   for (int i = 0; i < 16; ++i) kr[i] = kp[(long)i * NINP];
; }
; DEV void hg_load_v(const u16* __restrict__ zb, int wid, int lane, u16 (&vr)[8]) {
;   const u16* vp = zb + (long)(wid * 8) * NINP + C_HI + lane;
; #pragma unroll
;   for (int i = 0; i < 8; ++i) vr[i] = vp[(long)i * NINP];
; }
.LBB0_731:
	s_or_b64 exec, exec, s[6:7]
	v_readlane_b32 s6, v253, 23
	v_readlane_b32 s7, v253, 24
	s_waitcnt lgkmcnt(0)
	v_mov_b32_e32 v0, v197
	s_and_b64 vcc, exec, s[6:7]
	s_barrier
	s_cbranch_vccz .LBB0_744
	v_lshrrev_b32_e32 v1, 2, v0
	v_and_b32_e32 v1, 48, v1
	v_mul_u32_u24_e32 v10, 0x2200, v1
	v_lshlrev_b32_e32 v1, 1, v0
	v_readlane_b32 s6, v254, 14
	v_and_b32_e32 v32, 0xfffffe00, v1
	v_lshlrev_b32_e32 v156, 1, v10
	v_readlane_b32 s7, v254, 15
	v_and_b32_e32 v8, 63, v0
	v_ashrrev_i32_e32 v33, 31, v32
	v_lshl_add_u64 v[2:3], s[6:7], 0, v[156:157]
	v_lshl_add_u64 v[2:3], v[32:33], 1, v[2:3]
	v_lshlrev_b32_e32 v156, 1, v8
	v_lshl_add_u64 v[2:3], v[2:3], 0, v[156:157]
	s_mov_b32 s6, 0x40000
	v_add_co_u32_e32 v4, vcc, s6, v2
	s_mov_b32 s6, 0x3c000
	s_nop 0
	v_addc_co_u32_e32 v5, vcc, 0, v3, vcc
	global_load_ushort v6, v[4:5], off offset:2880
	v_add_co_u32_e32 v4, vcc, s6, v2
	s_mov_b32 s6, 0x38000
	s_nop 0
	v_addc_co_u32_e32 v5, vcc, 0, v3, vcc
	global_load_ushort v7, v[4:5], off offset:1856
	v_add_co_u32_e32 v4, vcc, s6, v2
	s_mov_b32 s6, 0x33000
	s_nop 0
	v_addc_co_u32_e32 v5, vcc, 0, v3, vcc
	global_load_ushort v9, v[4:5], off offset:832
	v_add_co_u32_e32 v4, vcc, s6, v2
	s_mov_b32 s6, 0x2f000
	s_nop 0
	v_addc_co_u32_e32 v5, vcc, 0, v3, vcc
	global_load_ushort v11, v[4:5], off offset:3904
	v_add_co_u32_e32 v4, vcc, s6, v2
	s_mov_b32 s6, 0x2b000
	s_nop 0
	v_addc_co_u32_e32 v5, vcc, 0, v3, vcc
	global_load_ushort v14, v[4:5], off offset:2880
	v_add_co_u32_e32 v4, vcc, s6, v2
	s_mov_b32 s6, 0x27000
	s_nop 0
	v_addc_co_u32_e32 v5, vcc, 0, v3, vcc
	global_load_ushort v15, v[4:5], off offset:1856
	v_add_co_u32_e32 v4, vcc, s6, v2
	s_mov_b32 s6, 0x22000
	s_nop 0
	v_addc_co_u32_e32 v5, vcc, 0, v3, vcc
	global_load_ushort v16, v[4:5], off offset:832
	v_add_co_u32_e32 v4, vcc, s6, v2
	s_mov_b32 s6, 0x1e000
	s_nop 0
	v_addc_co_u32_e32 v5, vcc, 0, v3, vcc
	global_load_ushort v17, v[4:5], off offset:3904
	v_add_co_u32_e32 v4, vcc, s6, v2
	s_mov_b32 s6, 0x11000
	s_nop 0
	v_addc_co_u32_e32 v5, vcc, 0, v3, vcc
	global_load_ushort v18, v[4:5], off offset:2880
	v_add_co_u32_e32 v4, vcc, s73, v2
	v_ashrrev_i32_e32 v1, 6, v0
	s_nop 0
	v_addc_co_u32_e32 v5, vcc, 0, v3, vcc
	global_load_ushort v19, v[4:5], off offset:1856
	v_add_co_u32_e32 v4, vcc, s68, v2
	v_ashrrev_i32_e32 v58, 8, v0
	s_nop 0
	v_addc_co_u32_e32 v5, vcc, 0, v3, vcc
	global_load_ushort v20, v[4:5], off offset:832
	v_add_co_u32_e32 v4, vcc, s6, v2
	s_mov_b32 s6, 0xd000
	s_nop 0
	v_addc_co_u32_e32 v5, vcc, 0, v3, vcc
	global_load_ushort v21, v[4:5], off offset:3904
	v_add_co_u32_e32 v4, vcc, s6, v2
	s_mov_b32 s6, 0x9000
	s_nop 0
	v_addc_co_u32_e32 v5, vcc, 0, v3, vcc
	global_load_ushort v22, v[4:5], off offset:2880
	v_add_co_u32_e32 v4, vcc, s6, v2
	s_movk_i32 s6, 0x5000
	s_nop 0
	v_addc_co_u32_e32 v5, vcc, 0, v3, vcc
	global_load_ushort v23, v[4:5], off offset:1856
	v_add_co_u32_e32 v4, vcc, s6, v2
	v_lshlrev_b32_e32 v156, 2, v8
	s_nop 0
	v_addc_co_u32_e32 v5, vcc, 0, v3, vcc
	global_load_ushort v24, v[4:5], off offset:832
	global_load_ushort v25, v[2:3], off offset:3904
	v_and_b32_e32 v2, 3, v1
	v_lshlrev_b32_e32 v3, 3, v1
	v_mad_i64_i32 v[34:35], s[6:7], v3, s33, 0
	v_readlane_b32 s52, v254, 14
	v_readlane_b32 s53, v254, 15
	v_lshlrev_b32_e32 v112, 1, v8
	v_add_u32_e32 v112, v112, v34
	v_add_u32_e32 v113, s69, v112
	v_add_u32_e32 v114, 0x9000, v112
	v_add_u32_e32 v115, 0xd000, v112
	v_add_u32_e32 v116, 0x11000, v112
	v_add_u32_e32 v117, 0x15000, v112
	v_add_u32_e32 v118, s73, v112
	v_add_u32_e32 v119, 0x1e000, v112
	global_load_ushort v104, v112, s[52:53] offset:2880
	global_load_ushort v105, v113, s[52:53] offset:3904
	global_load_ushort v106, v114, s[52:53] offset:832
	global_load_ushort v107, v115, s[52:53] offset:1856
	global_load_ushort v108, v116, s[52:53] offset:2880
	global_load_ushort v109, v117, s[52:53] offset:3904
	global_load_ushort v110, v118, s[52:53] offset:832
	global_load_ushort v111, v119, s[52:53] offset:1856
	v_lshlrev_b32_e32 v3, 10, v58
	v_lshlrev_b32_e32 v4, 8, v2
	v_or3_b32 v3, v3, v4, v156
	v_mov_b32_e32 v4, 0x12000
	v_lshlrev_b32_e32 v27, 4, v1
	v_and_b32_e32 v1, 0x3fffff00, v0
	v_mad_u32_u24 v26, v8, s74, v4
	v_lshl_or_b32 v1, v1, 2, v156
	v_and_b32_e32 v4, 15, v0
	v_cmp_gt_u32_e64 s[38:39], s72, v0
	v_cmp_lt_u32_e64 s[40:41], s67, v0
	v_add_u32_e32 v59, 0x14400, v3
	v_mul_u32_u24_e32 v3, 0x90, v8
	v_add_u32_e32 v60, 0x14400, v1
	s_movk_i32 s6, 0x2400
	v_lshlrev_b32_e32 v12, 5, v2
	v_lshl_or_b32 v1, v2, 4, v4
	v_and_b32_e32 v29, 48, v0
	v_mov_b32_e32 v13, v157
	v_lshrrev_b32_e32 v0, 1, v0
	v_cmp_eq_u32_e64 s[42:43], 3, v2
	v_cmp_gt_u32_e64 s[44:45], 2, v2
	v_cmp_eq_u32_e64 s[46:47], 0, v2
	v_cmp_lt_u32_e64 s[48:49], 1, v2
	v_mad_i32_i24 v28, v58, s6, v3
	v_lshl_add_u64 v[36:37], s[20:21], 0, v[156:157]
	v_mul_u32_u24_e32 v1, 0x90, v1
	v_lshl_add_u64 v[2:3], s[22:23], 0, v[12:13]
	v_and_b32_e32 v156, 24, v0
	v_mad_i32_i24 v30, v58, s6, v1
	v_or_b32_e32 v31, 0x12000, v29
	v_mul_u32_u24_e32 v41, 0x90, v4
	v_lshl_add_u64 v[0:1], v[2:3], 0, v[156:157]
	v_lshlrev_b32_e32 v156, 7, v4
	s_mov_b32 s6, 0x5040100
	v_lshl_add_u64 v[38:39], v[0:1], 0, v[156:157]
	s_waitcnt vmcnt(22)
	v_perm_b32 v1, v6, v7, s6
	s_waitcnt vmcnt(20)
	v_perm_b32 v2, v9, v11, s6
	s_waitcnt vmcnt(18)
	v_perm_b32 v3, v14, v15, s6
	s_waitcnt vmcnt(16)
	v_perm_b32 v4, v16, v17, s6
	v_lshlrev_b32_e32 v156, 1, v10
	v_lshlrev_b32_e32 v40, 1, v8
	v_add_u32_e32 v61, v26, v27
	v_add_u32_e32 v62, v28, v12
	v_add_u32_e32 v63, v30, v29
	s_waitcnt vmcnt(14)
	v_perm_b32 v5, v18, v19, s6
	v_add_u32_e32 v64, v31, v41
	s_mov_b32 s10, s75
	s_waitcnt vmcnt(12)
	v_perm_b32 v6, v20, v21, s6
	s_waitcnt vmcnt(10)
	v_perm_b32 v7, v22, v23, s6
	s_waitcnt vmcnt(8)
	v_perm_b32 v0, v24, v25, s6
	s_waitcnt vmcnt(0)
	v_perm_b32 v99, v111, v110, s6
	v_perm_b32 v98, v109, v108, s6
	v_perm_b32 v97, v107, v106, s6
	v_perm_b32 v96, v105, v104, s6
	s_branch .LBB0_734
; #define MFMA16(a, b, c) __builtin_amdgcn_mfma_f32_16x16x32_bf16(a, b, c, 0, 0, 0)
; DEV void hg_load_v(const u16* __restrict__ zb, int wid, int lane, u16 (&vr)[8]) {
;   const u16* vp = zb + (long)(wid * 8) * NINP + C_HI + lane;
; #pragma unroll
;   for (int i = 0; i < 8; ++i) vr[i] = vp[(long)i * NINP];
; }
; DEV void hg1_item(const Params& p, int item, char* smem, int tid, const u16 (&kr)[16]) {
;     ...
;   f32x4 acc[4];
; #pragma unroll
;   for (int vt = 0; vt < 4; ++vt) acc[vt] = f32x4{0.f, 0.f, 0.f, 0.f};
; #pragma unroll
;   for (int ks = 0; ks < 2; ++ks) {
;     const int ao = dir * 9216 + (qu * 16 + fr) * HROW + ks * 64 + fq * 16;
;     const bf16x8 ah = *(const bf16x8*)(smem + H_KH + ao);
; #pragma unroll
;     for (int vt = 0; vt < 4; ++vt) {
;       const bf16x8 b = *(const bf16x8*)(smem + H_VT + (vt * 16 + fr) * HROW + ks * 64 + fq * 16);
;       acc[vt] = MFMA16(ah, b, acc[vt]);
;     }
;   }
;   u16* so = p.Sloc + slot * 4096;
; #pragma unroll
;   for (int vt = 0; vt < 4; ++vt) {
;     uint2 o2;
;     o2.x = pack2(acc[vt][0], acc[vt][1]);
;     o2.y = pack2(acc[vt][2], acc[vt][3]);
;     *(uint2*)(so + (vt * 16 + fr) * 64 + qu * 16 + fq * 4) = o2;
;   }
.LBB0_733:
	s_or_b64 exec, exec, s[8:9]
	s_waitcnt lgkmcnt(0)
	s_barrier
	ds_read_b128 v[2:5], v63 offset:36864
	ds_read_b128 v[6:9], v64
	ds_read_b128 v[10:13], v64 offset:2304
	ds_read_b128 v[14:17], v64 offset:4608
	ds_read_b128 v[18:21], v64 offset:6912
	s_waitcnt lgkmcnt(3)
	v_mfma_f32_16x16x32_bf16 v[6:9], v[2:5], v[6:9], 0
	v_lshlrev_b64 v[0:1], 13, v[0:1]
	v_lshl_add_u64 v[0:1], v[38:39], 0, v[0:1]
	s_mov_b32 s8, 0x5040100
	s_waitcnt lgkmcnt(2)
	v_mfma_f32_16x16x32_bf16 v[10:13], v[2:5], v[10:13], 0
	s_waitcnt lgkmcnt(1)
	v_mfma_f32_16x16x32_bf16 v[14:17], v[2:5], v[14:17], 0
	s_waitcnt lgkmcnt(0)
	v_mfma_f32_16x16x32_bf16 v[2:5], v[2:5], v[18:21], 0
	ds_read_b128 v[18:21], v63 offset:36928
	ds_read_b128 v[22:25], v64 offset:64
	s_waitcnt lgkmcnt(0)
	v_mfma_f32_16x16x32_bf16 v[6:9], v[18:21], v[22:25], v[6:9]
	ds_read_b128 v[22:25], v64 offset:2368
	s_waitcnt lgkmcnt(0)
	v_mfma_f32_16x16x32_bf16 v[10:13], v[18:21], v[22:25], v[10:13]
	ds_read_b128 v[22:25], v64 offset:4672
	s_nop 3
	v_cvt_pk_bf16_f32 v6, v6, v7
	v_cvt_pk_bf16_f32 v7, v8, v9
	s_waitcnt lgkmcnt(0)
	v_mfma_f32_16x16x32_bf16 v[14:17], v[18:21], v[22:25], v[14:17]
	ds_read_b128 v[22:25], v64 offset:6976
	global_store_dwordx2 v[0:1], v[6:7], off
	v_cvt_pk_bf16_f32 v6, v10, v11
	s_waitcnt lgkmcnt(0)
	v_mfma_f32_16x16x32_bf16 v[2:5], v[18:21], v[22:25], v[2:5]
	v_cvt_pk_bf16_f32 v7, v12, v13
	global_store_dwordx2 v[0:1], v[6:7], off offset:2048
	v_add_co_u32_e32 v0, vcc, s71, v0
	v_cvt_pk_bf16_f32 v6, v14, v15
	v_cvt_pk_bf16_f32 v7, v16, v17
	v_addc_co_u32_e32 v1, vcc, 0, v1, vcc
	s_nop 1
	v_cvt_pk_bf16_f32 v2, v2, v3
	v_cvt_pk_bf16_f32 v3, v4, v5
	global_store_dwordx2 v[0:1], v[6:7], off
	global_store_dwordx2 v[0:1], v[2:3], off offset:2048
	s_waitcnt vmcnt(4)
	v_perm_b32 v1, v80, v79, s8
	v_perm_b32 v2, v78, v77, s8
	v_perm_b32 v3, v76, v75, s8
	v_perm_b32 v4, v74, v73, s8
	v_perm_b32 v5, v72, v71, s8
	v_perm_b32 v6, v70, v69, s8
	v_perm_b32 v7, v68, v67, s8
	v_perm_b32 v0, v66, v65, s8
	v_perm_b32 v99, v87, v86, s8
	v_perm_b32 v98, v85, v84, s8
	v_perm_b32 v97, v83, v82, s8
	v_perm_b32 v96, v81, v41, s8
	s_and_b64 vcc, exec, s[6:7]
	s_cbranch_vccnz .LBB0_744
.LBB0_734:
	v_readlane_b32 s6, v253, 2
	s_mov_b32 s11, s10
	s_add_i32 s10, s10, s6
	v_readlane_b32 s7, v253, 3
	s_cmpk_gt_i32 s10, 0x8ff
	s_cselect_b64 s[6:7], -1, 0
	s_cmpk_lt_i32 s10, 0x900
	s_cselect_b32 s8, s10, s11
	s_mov_b32 s50, s8
	s_mov_b32 s19, 0x9000
	s_mov_b32 s18, 0xd000
	s_mov_b32 s17, 0x11000
	s_mov_b32 s16, 0x1e000
	s_ashr_i32 s9, s11, 3
	s_and_b32 s8, s11, 7
	s_mul_hi_i32 s11, s9, 0x38e38e39
	s_lshr_b32 s12, s11, 31
	s_ashr_i32 s11, s11, 3
	s_add_i32 s11, s11, s12
	s_lshl_b32 s12, s11, 3
	s_or_b32 s8, s12, s8
	s_mul_i32 s11, s11, 36
	s_mul_i32 s8, s8, 36
	s_sub_i32 s9, s9, s11
	s_add_i32 s8, s8, s9
	s_mul_hi_i32 s9, s8, 0x38e38e39
	s_lshr_b32 s11, s9, 31
	s_ashr_i32 s9, s9, 3
	s_add_i32 s11, s9, s11
	s_mul_i32 s9, s11, 36
	s_sub_i32 s12, s8, s9
	s_ashr_i32 s8, s11, 3
	s_lshl_b32 s13, s12, 6
	s_mul_hi_i32 s9, s8, 0x900
	s_mulk_i32 s8, 0x900
	s_ashr_i32 s15, s13, 31
	s_add_u32 s8, s8, s13
	s_addc_u32 s9, s9, s15
	s_mulk_i32 s9, 0x4400
	s_mul_hi_u32 s13, s8, 0x4400
	s_add_i32 s13, s13, s9
	s_mulk_i32 s8, 0x4400
	s_add_u32 s8, s88, s8
	s_addc_u32 s9, s89, s13
	s_lshl_b32 s13, s11, 7
	s_and_b32 s13, s13, 0x380
	s_add_u32 s8, s8, s13
	s_addc_u32 s9, s9, 0
	v_lshlrev_b32_e32 v56, 16, v7
	v_and_b32_e32 v57, 0xffff0000, v7
	v_sub_f32_e32 v7, 1.0, v56
	v_log_f32_e32 v7, v7
	v_lshlrev_b32_e32 v46, 16, v6
	v_and_b32_e32 v47, 0xffff0000, v6
	s_mov_b32 s8, s50
	s_and_b32 s9, s8, 7
	s_ashr_i32 s8, s8, 3
	s_mul_hi_i32 s51, s8, 0x38e38e39
	s_lshr_b32 s13, s51, 31
	s_ashr_i32 s51, s51, 3
	s_add_i32 s51, s51, s13
	s_lshl_b32 s13, s51, 3
	s_or_b32 s9, s13, s9
	s_mul_i32 s51, s51, 36
	s_mul_i32 s9, s9, 36
	s_sub_i32 s8, s8, s51
	s_add_i32 s9, s9, s8
	s_mul_hi_i32 s8, s9, 0x38e38e39
	s_lshr_b32 s51, s8, 31
	s_ashr_i32 s8, s8, 3
	s_add_i32 s8, s8, s51
	s_mul_i32 s51, s8, 36
	s_sub_i32 s9, s9, s51
	s_ashr_i32 s51, s8, 3
	s_lshl_b32 s9, s9, 6
	s_mul_hi_i32 s13, s51, 0x900
	s_mulk_i32 s51, 0x900
	s_ashr_i32 s15, s9, 31
	s_add_u32 s9, s51, s9
	s_addc_u32 s51, s13, s15
	s_mulk_i32 s51, 0x4400
	s_mul_hi_u32 s13, s9, 0x4400
	s_add_i32 s13, s13, s51
	s_mulk_i32 s9, 0x4400
	s_add_u32 s9, s88, s9
	s_addc_u32 s51, s89, s13
	s_lshl_b32 s8, s8, 7
	s_and_b32 s8, s8, 0x380
	s_add_u32 s8, s9, s8
	s_addc_u32 s9, s51, 0
	global_load_ushort v41, v112, s[8:9] offset:2880
	global_load_ushort v81, v113, s[8:9] offset:3904
	global_load_ushort v82, v114, s[8:9] offset:832
	global_load_ushort v83, v115, s[8:9] offset:1856
	global_load_ushort v84, v116, s[8:9] offset:2880
	global_load_ushort v85, v117, s[8:9] offset:3904
	global_load_ushort v86, v118, s[8:9] offset:832
	global_load_ushort v87, v119, s[8:9] offset:1856
	v_lshl_add_u64 v[8:9], s[8:9], 0, v[156:157]
	v_lshl_add_u64 v[8:9], v[32:33], 1, v[8:9]
	v_mov_b32_e32 v190, v40
	v_mov_b32_e32 v191, v157
	v_lshl_add_u64 v[8:9], v[8:9], 0, v[190:191]
	s_movk_i32 s8, 0x5000
	v_add_co_u32_e32 v10, vcc, s8, v8
	s_mov_b32 s19, 0x9000
	s_nop 0
	v_addc_co_u32_e32 v11, vcc, 0, v9, vcc
	v_add_co_u32_e32 v12, vcc, s19, v8
	s_mov_b32 s18, 0xd000
	s_nop 0
; DEV float bf2f(u16 h) { return __uint_as_float(((unsigned)h) << 16); }
; DEV float flog(float x) { return __builtin_amdgcn_logf(x) * 0.6931471805599453f; }
; DEV void hg_load_k(const u16* __restrict__ zb, int tid, u16 (&kr)[16]) {
;   const int wid = tid >> 6, lane = tid & 63, dir = wid >> 2, qu = wid & 3;
;   const u16* kp = zb + (long)(qu * 16) * NINP + C_HF + dir * 512 + lane;
; #pragma unroll
;   for (int i = 0; i < 16; ++i) kr[i] = kp[(long)i * NINP];
; }
; DEV void hg_load_v(const u16* __restrict__ zb, int wid, int lane, u16 (&vr)[8]) {
;   const u16* vp = zb + (long)(wid * 8) * NINP + C_HI + lane;
; #pragma unroll
;   for (int i = 0; i < 8; ++i) vr[i] = vp[(long)i * NINP];
; }
; DEV void hg_prep(int dir, int qu, int lane, char* smem, const u16 (&kr)[16], float (&g)[16], float (&kk)[16]) {
; #pragma unroll
;   for (int i = 0; i < 16; ++i) {
;     kk[i] = bf2f(kr[i]);
;     g[i] = fmaxf(flog(1.f - kk[i]), -20.f);
;   }
;   float total;
;   if (dir == 0) {
; #pragma unroll
;     for (int i = 1; i < 16; ++i) g[i] += g[i - 1];
;     total = g[15];
;   } else {
; #pragma unroll
;     for (int i = 14; i >= 0; --i) g[i] += g[i + 1];
	v_addc_co_u32_e32 v13, vcc, 0, v9, vcc
	v_add_co_u32_e32 v14, vcc, s18, v8
	s_mov_b32 s17, 0x11000
	s_nop 0
	v_addc_co_u32_e32 v15, vcc, 0, v9, vcc
	v_add_co_u32_e32 v16, vcc, s17, v8
	s_mov_b32 s16, 0x1e000
	s_nop 0
	v_addc_co_u32_e32 v17, vcc, 0, v9, vcc
	v_add_co_u32_e32 v18, vcc, s68, v8
	s_mov_b32 s8, 0x22000
	s_nop 0
	v_addc_co_u32_e32 v19, vcc, 0, v9, vcc
	v_add_co_u32_e32 v20, vcc, s73, v8
	s_nop 0
	v_addc_co_u32_e32 v21, vcc, 0, v9, vcc
	v_add_co_u32_e32 v22, vcc, s16, v8
	v_and_b32_e32 v49, 0xffff0000, v0
	s_nop 0
	v_addc_co_u32_e32 v23, vcc, 0, v9, vcc
	global_load_ushort v65, v[8:9], off offset:3904
	global_load_ushort v66, v[10:11], off offset:832
	global_load_ushort v67, v[12:13], off offset:1856
	global_load_ushort v68, v[14:15], off offset:2880
	global_load_ushort v69, v[16:17], off offset:3904
	global_load_ushort v70, v[18:19], off offset:832
	global_load_ushort v71, v[20:21], off offset:1856
	global_load_ushort v72, v[22:23], off offset:2880
	v_add_co_u32_e32 v10, vcc, s8, v8
	s_mov_b32 s8, 0x27000
	s_nop 0
	v_addc_co_u32_e32 v11, vcc, 0, v9, vcc
	v_add_co_u32_e32 v12, vcc, s8, v8
	s_mov_b32 s8, 0x2b000
	s_nop 0
	v_addc_co_u32_e32 v13, vcc, 0, v9, vcc
	v_add_co_u32_e32 v14, vcc, s8, v8
	s_mov_b32 s8, 0x2f000
	s_nop 0
	v_addc_co_u32_e32 v15, vcc, 0, v9, vcc
	v_add_co_u32_e32 v16, vcc, s8, v8
	s_mov_b32 s8, 0x33000
	s_nop 0
	v_addc_co_u32_e32 v17, vcc, 0, v9, vcc
	v_add_co_u32_e32 v18, vcc, s8, v8
	s_mov_b32 s8, 0x38000
	s_nop 0
	v_addc_co_u32_e32 v19, vcc, 0, v9, vcc
	v_add_co_u32_e32 v20, vcc, s8, v8
	s_mov_b32 s8, 0x3c000
	s_nop 0
	v_addc_co_u32_e32 v21, vcc, 0, v9, vcc
	v_add_co_u32_e32 v22, vcc, s8, v8
	s_mov_b32 s8, 0x40000
	s_nop 0
	v_addc_co_u32_e32 v23, vcc, 0, v9, vcc
	v_add_co_u32_e32 v8, vcc, s8, v8
	v_addc_co_u32_e32 v9, vcc, 0, v9, vcc
	global_load_ushort v73, v[10:11], off offset:3904
	global_load_ushort v74, v[12:13], off offset:832
	global_load_ushort v75, v[14:15], off offset:1856
	global_load_ushort v76, v[16:17], off offset:2880
	global_load_ushort v77, v[18:19], off offset:3904
	global_load_ushort v78, v[20:21], off offset:832
	global_load_ushort v79, v[22:23], off offset:1856
	global_load_ushort v80, v[8:9], off offset:2880
	v_sub_f32_e32 v8, 1.0, v49
	v_log_f32_e32 v8, v8
	v_sub_f32_e32 v9, 1.0, v57
	v_log_f32_e32 v9, v9
	v_sub_f32_e32 v6, 1.0, v46
	v_mul_f32_e32 v8, 0x3f317218, v8
	v_max_f32_e32 v88, 0xc1a00000, v8
	v_log_f32_e32 v6, v6
	v_sub_f32_e32 v8, 1.0, v47
	v_log_f32_e32 v8, v8
	v_mul_f32_e32 v7, 0x3f317218, v7
	v_lshlrev_b32_e32 v54, 16, v5
	v_max_f32_e32 v89, 0xc1a00000, v7
	v_mul_f32_e32 v7, 0x3f317218, v9
	v_and_b32_e32 v55, 0xffff0000, v5
	v_sub_f32_e32 v5, 1.0, v54
	v_max_f32_e32 v90, 0xc1a00000, v7
	v_mul_f32_e32 v6, 0x3f317218, v6
	v_log_f32_e32 v7, v5
	v_sub_f32_e32 v5, 1.0, v55
	v_max_f32_e32 v91, 0xc1a00000, v6
	v_mul_f32_e32 v6, 0x3f317218, v8
	v_log_f32_e32 v8, v5
	v_lshlrev_b32_e32 v44, 16, v4
	v_and_b32_e32 v45, 0xffff0000, v4
	v_sub_f32_e32 v4, 1.0, v44
	v_max_f32_e32 v5, 0xc1a00000, v6
	v_mul_f32_e32 v6, 0x3f317218, v7
	v_mul_f32_e32 v7, 0x3f317218, v8
	v_log_f32_e32 v4, v4
	v_sub_f32_e32 v8, 1.0, v45
	v_log_f32_e32 v9, v8
	v_lshlrev_b32_e32 v52, 16, v3
	v_mul_f32_e32 v4, 0x3f317218, v4
	v_and_b32_e32 v53, 0xffff0000, v3
	v_sub_f32_e32 v3, 1.0, v52
	v_max_f32_e32 v8, 0xc1a00000, v4
	v_mul_f32_e32 v4, 0x3f317218, v9
	v_log_f32_e32 v3, v3
	v_sub_f32_e32 v9, 1.0, v53
	v_log_f32_e32 v11, v9
	v_lshlrev_b32_e32 v42, 16, v2
	v_mul_f32_e32 v3, 0x3f317218, v3
	v_lshlrev_b32_e32 v50, 16, v1
	v_lshlrev_b32_e32 v48, 16, v0
	v_max_f32_e32 v10, 0xc1a00000, v3
	v_mul_f32_e32 v3, 0x3f317218, v11
	v_and_b32_e32 v43, 0xffff0000, v2
	v_sub_f32_e32 v2, 1.0, v42
	v_and_b32_e32 v51, 0xffff0000, v1
	v_sub_f32_e32 v1, 1.0, v50
	v_sub_f32_e32 v0, 1.0, v48
	v_max_f32_e32 v9, 0xc1a00000, v4
	v_log_f32_e32 v2, v2
	v_sub_f32_e32 v4, 1.0, v43
	v_max_f32_e32 v11, 0xc1a00000, v3
	v_log_f32_e32 v1, v1
	v_sub_f32_e32 v3, 1.0, v51
	v_log_f32_e32 v0, v0
	v_log_f32_e32 v4, v4
	v_log_f32_e32 v3, v3
	v_mul_f32_e32 v2, 0x3f317218, v2
	v_mul_f32_e32 v1, 0x3f317218, v1
	v_mul_f32_e32 v0, 0x3f317218, v0
	v_max_f32_e32 v12, 0xc1a00000, v2
	v_mul_f32_e32 v2, 0x3f317218, v4
	v_max_f32_e32 v14, 0xc1a00000, v1
	v_mul_f32_e32 v1, 0x3f317218, v3
	v_max_f32_e32 v0, 0xc1a00000, v0
	v_max_f32_e32 v6, 0xc1a00000, v6
	v_max_f32_e32 v7, 0xc1a00000, v7
	v_max_f32_e32 v13, 0xc1a00000, v2
	v_max_f32_e32 v15, 0xc1a00000, v1
	s_barrier
	s_and_saveexec_b64 s[8:9], s[40:41]
	s_xor_b64 s[8:9], exec, s[8:9]
	s_cbranch_execz .LBB0_736
	v_add_f32_e32 v14, v14, v15
	v_add_f32_e32 v13, v13, v14
	v_add_f32_e32 v12, v12, v13
	v_add_f32_e32 v11, v11, v12
	v_add_f32_e32 v10, v10, v11
	v_add_f32_e32 v9, v9, v10
	v_add_f32_e32 v8, v8, v9
	v_add_f32_e32 v7, v7, v8
	v_add_f32_e32 v6, v6, v7
	v_add_f32_e32 v5, v5, v6
	v_add_f32_e32 v4, v91, v5
	v_add_f32_e32 v3, v90, v4
	v_add_f32_e32 v2, v89, v3
	v_add_f32_e32 v1, v88, v2
	v_add_f32_e32 v0, v0, v1
	v_mov_b64_e32 v[30:31], v[14:15]
	v_mov_b64_e32 v[28:29], v[12:13]
	v_mov_b64_e32 v[26:27], v[10:11]
	v_mov_b64_e32 v[24:25], v[8:9]
	v_mov_b64_e32 v[22:23], v[6:7]
	v_mov_b64_e32 v[20:21], v[4:5]
	v_mov_b64_e32 v[18:19], v[2:3]
	v_mov_b64_e32 v[16:17], v[0:1]

; DEV void hg1_item(const Params& p, int item, char* smem, int tid, const u16 (&kr)[16]) {
;     ...
;   hg_prep(dir, qu, lane, smem, kr, g, kk);
;   __syncthreads();
;   hg_store_vt(wid, lane, smem, vr);
;   const float* tot = (const float*)(smem + H_TOT) + dir * 256 + lane;
;   const float t0 = tot[0], t1 = tot[64], t2 = tot[128], t3 = tot[192];
;   const float T = (t0 + t1) + (t2 + t3);
;   float off;
;   if (dir == 0) off = (qu > 0 ? t0 : 0.f) + (qu > 1 ? t1 : 0.f) + (qu > 2 ? t2 : 0.f);
;   else off = (qu < 3 ? t3 : 0.f) + (qu < 2 ? t2 : 0.f) + (qu < 1 ? t1 : 0.f);
.LBB0_738:
	s_or_b64 exec, exec, s[8:9]
	s_mov_b32 s8, 0x5040100
	ds_write_b32 v59, v0
	s_waitcnt lgkmcnt(0)
	s_barrier
	ds_write_b128 v61, v[96:99]
	ds_read2st64_b32 v[0:1], v60 offset1:1
	ds_read2st64_b32 v[2:3], v60 offset0:2 offset1:3
	s_and_saveexec_b64 s[8:9], s[40:41]
	s_xor_b64 s[8:9], exec, s[8:9]
	s_cbranch_execz .LBB0_740
	s_waitcnt lgkmcnt(0)
	v_cndmask_b32_e64 v4, v3, 0, s[42:43]
	v_cndmask_b32_e64 v5, 0, v2, s[44:45]
	v_add_f32_e32 v4, v5, v4
	v_cndmask_b32_e64 v5, 0, v1, s[46:47]
	v_add_f32_e32 v4, v5, v4
